# GDN chain section D: the two products with the structurally zero upper-right block of the lower-triangular T are not formed (2 MFMAs and 2 LDS reads fewer per chunk and wave)
# baseline (speedup 1.0000x reference)
; #define LAS __attribute__((address_space(3)))
; __device__ __forceinline__ unsigned pk2(float lo, float hi) { const f32v2_t f = {lo, hi}; const bf16v2_t b = __builtin_convertvector(f, bf16v2_t); return __builtin_bit_cast(unsigned, b); }
; #define WAVE_SYNC() do { asm volatile("s_waitcnt lgkmcnt(0)" ::: "memory"); __builtin_amdgcn_wave_barrier(); asm volatile("" ::: "memory"); } while (0)
; #define MFMA16(a, b, c) __builtin_amdgcn_mfma_f32_16x16x32_bf16((a), (b), (c), 0, 0, 0)
; template <int MODE>
; __device__ NOINL void chain_item(const LAS Params* lp, int l, int item, bool ctx_out, LAS unsigned char* lds) {
;     ...
; #pragma unroll
;         for (int dk = 0; dk < NDK; ++dk) { u32x2 pk; pk.x = pk2(Sacc[dk][0], Sacc[dk][1]); pk.y = pk2(Sacc[dk][2], Sacc[dk][3]); *(LAS u32x2*)(ST + fr * 136 + 16 * dk + 4 * fq) = pk; }
;         WAVE_SYNC();
;         f32x4 qs[4], ksm[4];
; #pragma unroll
;         for (int ct = 0; ct < 4; ++ct) { qs[ct] = (f32x4){0.f, 0.f, 0.f, 0.f}; ksm[ct] = (f32x4){0.f, 0.f, 0.f, 0.f}; }
; #pragma unroll
;         for (int ks = 0; ks < NKS; ++ks) {
;             const bf16x8 Bf = *(const LAS bf16x8*)(ST + fr * 136 + ks * 32 + fq * 8);
; #pragma unroll
;             for (int ct = 0; ct < 4; ++ct) {
;                 const bf16x8 Aq = *(const LAS bf16x8*)(Qs + (16 * ct + fr) * 136 + kcol + ks * 32 + fq * 8);
;                 qs[ct] = MFMA16(Aq, Bf, qs[ct]);
;                 if (MODE == 0) { const bf16x8 Ak = *(const LAS bf16x8*)(Ks + (16 * ct + fr) * 136 + ks * 32 + fq * 8); ksm[ct] = MFMA16(Ak, Bf, ksm[ct]); }
;             }
;         }
.LBB0_1141:
	s_or_b64 exec, exec, s[62:63]
	ds_write_b16 v178, v68
	v_cvt_pk_bf16_f32 v68, v28, v29
	v_cvt_pk_bf16_f32 v69, v30, v31
	v_cvt_pk_bf16_f32 v70, v40, v41
	v_cvt_pk_bf16_f32 v71, v42, v43
	ds_write2_b64 v113, v[68:69], v[70:71] offset1:4
	v_cvt_pk_bf16_f32 v68, v32, v33
	v_cvt_pk_bf16_f32 v69, v34, v35
	v_cvt_pk_bf16_f32 v70, v36, v37
	v_cvt_pk_bf16_f32 v71, v38, v39
	ds_write2_b64 v113, v[68:69], v[70:71] offset0:8 offset1:12
	v_cvt_pk_bf16_f32 v68, v56, v57
	v_cvt_pk_bf16_f32 v69, v58, v59
	v_cvt_pk_bf16_f32 v70, v52, v53
	v_cvt_pk_bf16_f32 v71, v54, v55
	ds_write2_b64 v113, v[68:69], v[70:71] offset0:16 offset1:20
	v_cvt_pk_bf16_f32 v68, v44, v45
	v_cvt_pk_bf16_f32 v69, v46, v47
	v_cvt_pk_bf16_f32 v70, v48, v49
	v_cvt_pk_bf16_f32 v71, v50, v51
	ds_write2_b64 v113, v[68:69], v[70:71] offset0:24 offset1:28
	s_waitcnt lgkmcnt(0)
	v_add_u32_e32 v119, v113, v154
	ds_read_b128 v[84:87], v119
	ds_read_b128 v[100:103], v179
	ds_read_b128 v[104:107], v179 offset:17408
	ds_read_b128 v[194:197], v179 offset:4352
	ds_read_b128 v[236:239], v179 offset:21760
	ds_read_b128 v[240:243], v179 offset:8704
	ds_read_b128 v[244:247], v179 offset:26112
	ds_read_b128 v[248:251], v179 offset:13056
	v_add_u32_e32 v121, 0x25500, v110
	s_waitcnt lgkmcnt(6)
	v_mfma_f32_16x16x32_bf16 v[96:99], v[100:103], v[84:87], 0
	ds_read_b128 v[100:103], v179 offset:30464
	ds_read_b128 v[88:91], v119 offset:64
	s_add_i32 s5, s4, 4
	s_waitcnt lgkmcnt(7)
	v_mfma_f32_16x16x32_bf16 v[198:201], v[104:107], v[84:87], 0
	ds_read_b128 v[104:107], v179 offset:64
	s_and_b64 s[20:21], vcc, exec
	s_waitcnt lgkmcnt(7)
	v_mfma_f32_16x16x32_bf16 v[92:95], v[194:197], v[84:87], 0
	ds_read_b128 v[194:197], v179 offset:17472
	s_cselect_b32 s5, s1, s5
	s_waitcnt lgkmcnt(7)
	v_mfma_f32_16x16x32_bf16 v[232:235], v[236:239], v[84:87], 0
	ds_read_b128 v[236:239], v179 offset:4416
	s_add_i32 s22, s4, 40
	s_waitcnt lgkmcnt(7)
	v_mfma_f32_16x16x32_bf16 v[80:83], v[240:243], v[84:87], 0
	ds_read_b128 v[240:243], v179 offset:21824
	s_and_b64 s[20:21], vcc, exec
	s_waitcnt lgkmcnt(7)
	v_mfma_f32_16x16x32_bf16 v[72:75], v[244:247], v[84:87], 0
	ds_read_b128 v[244:247], v179 offset:8768
	s_cselect_b32 s20, s1, s22
	s_waitcnt lgkmcnt(7)
	v_mfma_f32_16x16x32_bf16 v[76:79], v[248:251], v[84:87], 0
	ds_read_b128 v[248:251], v179 offset:26176
	s_cmp_lt_u32 s1, 4
	s_waitcnt lgkmcnt(7)
	v_mfma_f32_16x16x32_bf16 v[68:71], v[100:103], v[84:87], 0
	ds_read_b128 v[100:103], v179 offset:13120
	s_cselect_b32 s1, s5, s20
	s_waitcnt lgkmcnt(6)
	v_mfma_f32_16x16x32_bf16 v[96:99], v[104:107], v[88:91], v[96:99]
	ds_read_b128 v[104:107], v179 offset:30528
	ds_read_b128 v[84:87], v119 offset:128
	s_lshl_b32 s5, s1, 6
	s_waitcnt lgkmcnt(7)
	v_mfma_f32_16x16x32_bf16 v[198:201], v[194:197], v[88:91], v[198:201]
	ds_read_b128 v[194:197], v179 offset:128
	s_add_i32 s20, s18, s5
	s_waitcnt lgkmcnt(7)
	v_mfma_f32_16x16x32_bf16 v[92:95], v[236:239], v[88:91], v[92:95]
	ds_read_b128 v[236:239], v179 offset:17536
	s_or_b32 s5, s5, s38
	s_waitcnt lgkmcnt(7)
	v_mfma_f32_16x16x32_bf16 v[232:235], v[240:243], v[88:91], v[232:235]
	ds_read_b128 v[240:243], v179 offset:4480
	s_cmp_lt_u32 s1, 4
	s_waitcnt lgkmcnt(7)
	v_mfma_f32_16x16x32_bf16 v[80:83], v[244:247], v[88:91], v[80:83]
	ds_read_b128 v[244:247], v179 offset:21888
	s_cselect_b32 s1, s5, s20
	s_waitcnt lgkmcnt(7)
	v_mfma_f32_16x16x32_bf16 v[72:75], v[248:251], v[88:91], v[72:75]
	ds_read_b128 v[248:251], v179 offset:8832
	s_mul_hi_i32 s21, s1, s19
	s_waitcnt lgkmcnt(7)
	v_mfma_f32_16x16x32_bf16 v[76:79], v[100:103], v[88:91], v[76:79]
	ds_read_b128 v[100:103], v179 offset:26240
	s_mul_i32 s20, s1, s19
	s_waitcnt lgkmcnt(7)
	v_mfma_f32_16x16x32_bf16 v[68:71], v[104:107], v[88:91], v[68:71]
	ds_read_b128 v[104:107], v179 offset:13184
	v_mov_b32_e32 v123, v1
	s_waitcnt lgkmcnt(6)
	v_mfma_f32_16x16x32_bf16 v[96:99], v[194:197], v[84:87], v[96:99]
	ds_read_b128 v[194:197], v179 offset:30592
	ds_read_b128 v[88:91], v119 offset:192
	v_add_u32_e32 v119, s34, v155
	v_mov_b32_e32 v125, v1
	s_waitcnt lgkmcnt(7)
	v_mfma_f32_16x16x32_bf16 v[198:201], v[236:239], v[84:87], v[198:201]
	ds_read_b128 v[236:239], v179 offset:192
	v_mov_b32_e32 v127, v1
	s_waitcnt lgkmcnt(7)
	v_mfma_f32_16x16x32_bf16 v[92:95], v[240:243], v[84:87], v[92:95]
	ds_read_b128 v[240:243], v179 offset:17600
	v_mov_b32_e32 v129, v1
	s_waitcnt lgkmcnt(7)
	v_mfma_f32_16x16x32_bf16 v[232:235], v[244:247], v[84:87], v[232:235]
	ds_read_b128 v[244:247], v179 offset:4544
	v_mov_b32_e32 v131, v1
	s_waitcnt lgkmcnt(7)
	v_mfma_f32_16x16x32_bf16 v[80:83], v[248:251], v[84:87], v[80:83]
	ds_read_b128 v[248:251], v179 offset:21952
	v_mov_b32_e32 v133, v1
	s_waitcnt lgkmcnt(7)
	v_mfma_f32_16x16x32_bf16 v[72:75], v[100:103], v[84:87], v[72:75]
	ds_read_b128 v[100:103], v179 offset:8896
	v_mov_b32_e32 v135, v1
	s_waitcnt lgkmcnt(7)
	v_mfma_f32_16x16x32_bf16 v[76:79], v[104:107], v[84:87], v[76:79]
	ds_read_b128 v[104:107], v179 offset:26304
	v_mov_b32_e32 v137, v1
	s_waitcnt lgkmcnt(7)
	v_mfma_f32_16x16x32_bf16 v[68:71], v[194:197], v[84:87], v[68:71]
	ds_read_b128 v[194:197], v179 offset:13248
	v_mov_b32_e32 v139, v1
	s_waitcnt lgkmcnt(6)
	v_mfma_f32_16x16x32_bf16 v[96:99], v[236:239], v[88:91], v[96:99]
	ds_read_b128 v[236:239], v179 offset:30656
	v_mov_b32_e32 v141, v1
	s_waitcnt lgkmcnt(6)
	v_mfma_f32_16x16x32_bf16 v[198:201], v[240:243], v[88:91], v[198:201]
	v_mov_b32_e32 v143, v1
	s_waitcnt lgkmcnt(5)
	v_mfma_f32_16x16x32_bf16 v[92:95], v[244:247], v[88:91], v[92:95]
	v_mov_b32_e32 v145, v1
	s_waitcnt lgkmcnt(4)
	v_mfma_f32_16x16x32_bf16 v[232:235], v[248:251], v[88:91], v[232:235]
	v_mov_b32_e32 v147, v1
	s_waitcnt lgkmcnt(3)
; #define LAS __attribute__((address_space(3)))
; __device__ __forceinline__ unsigned pk2(float lo, float hi) { const f32v2_t f = {lo, hi}; const bf16v2_t b = __builtin_convertvector(f, bf16v2_t); return __builtin_bit_cast(unsigned, b); }
; __device__ __forceinline__ float bflo(unsigned u) { return __uint_as_float(u << 16); }
; __device__ __forceinline__ float bfhi(unsigned u) { return __uint_as_float(u & 0xFFFF0000u); }
; #define WAVE_SYNC() do { asm volatile("s_waitcnt lgkmcnt(0)" ::: "memory"); __builtin_amdgcn_wave_barrier(); asm volatile("" ::: "memory"); } while (0)
; #define MFMA16(a, b, c) __builtin_amdgcn_mfma_f32_16x16x32_bf16((a), (b), (c), 0, 0, 0)
; template <int MODE>
; __device__ NOINL void chain_item(const LAS Params* lp, int l, int item, bool ctx_out, LAS unsigned char* lds) {
;     ...
;         if (MODE == 0) {
; #pragma unroll
;             for (int ct = 0; ct < 4; ++ct) {
;                 const u32x2 vv = *(const LAS u32x2*)(VT + (dvrow + fr) * 72 + (((2 * ct + (fq >> 1)) ^ vkey) << 3) + 4 * (fq & 1));
;                 const float v4[4] = {bflo(vv.x), bfhi(vv.x), bflo(vv.y), bfhi(vv.y)};
;                 float r[4];
; #pragma unroll
;                 for (int j = 0; j < 4; ++j) r[j] = bts[16 * ct + 4 * fq + j] * (v4[j] - eg[ct][j] * ksm[ct][j]);
;                 u32x2 pk; pk.x = pk2(r[0], r[1]); pk.y = pk2(r[2], r[3]);
;                 *(LAS u32x2*)(RP + fr * 72 + 16 * ct + 4 * fq) = pk;
;             }
;             WAVE_SYNC();
;             bf16x8 Br[2];
;             Br[0] = *(const LAS bf16x8*)(RP + fr * 72 + fq * 8); Br[1] = *(const LAS bf16x8*)(RP + fr * 72 + 32 + fq * 8);
;             f32x4 vn[4];
; #pragma unroll
;             for (int ct = 0; ct < 4; ++ct) {
;                 vn[ct] = (f32x4){0.f, 0.f, 0.f, 0.f};
; #pragma unroll
;                 for (int ks = 0; ks < 2; ++ks) { const bf16x8 A = *(const LAS bf16x8*)(TT + (16 * ct + fr) * 72 + ks * 32 + fq * 8); vn[ct] = MFMA16(A, Br[ks], vn[ct]); }
;             }
	v_mfma_f32_16x16x32_bf16 v[80:83], v[100:103], v[88:91], v[80:83]
	s_add_i32 s4, s4, -1
	s_waitcnt lgkmcnt(2)
	v_mfma_f32_16x16x32_bf16 v[72:75], v[104:107], v[88:91], v[72:75]
	s_cmp_lg_u32 s0, 36
	s_waitcnt lgkmcnt(1)
	v_mfma_f32_16x16x32_bf16 v[76:79], v[194:197], v[88:91], v[76:79]
	s_mov_b32 s1, s0
	s_waitcnt lgkmcnt(0)
	v_mfma_f32_16x16x32_bf16 v[68:71], v[236:239], v[88:91], v[68:71]
	ds_read_b64 v[88:89], v186 offset:53248
	ds_read_b128 v[104:107], v119 offset:512
	ds_read_b128 v[84:87], v121
	s_waitcnt lgkmcnt(2)
	v_lshlrev_b32_e32 v90, 16, v88
	v_and_b32_e32 v91, 0xffff0000, v88
	v_lshlrev_b32_e32 v88, 16, v89
	v_and_b32_e32 v89, 0xffff0000, v89
	s_waitcnt lgkmcnt(1)
	v_pk_fma_f32 v[90:91], v[198:199], v[104:105], v[90:91] neg_lo:[1,0,0] neg_hi:[1,0,0]
	v_pk_fma_f32 v[88:89], v[200:201], v[106:107], v[88:89] neg_lo:[1,0,0] neg_hi:[1,0,0]
	s_waitcnt lgkmcnt(0)
	v_pk_mul_f32 v[84:85], v[84:85], v[90:91]
	v_pk_mul_f32 v[86:87], v[86:87], v[88:89]
	v_cvt_pk_bf16_f32 v148, v84, v85
	v_cvt_pk_bf16_f32 v149, v86, v87
	ds_read_b128 v[100:103], v119 offset:576
	ds_read_b128 v[88:91], v119 offset:640
	ds_read_b128 v[84:87], v119 offset:704
	ds_write_b64 v158, v[148:149] offset:4352
	ds_read_b64 v[148:149], v187 offset:53248
	ds_read_b128 v[194:197], v121 offset:64
	v_add_u32_e32 v119, v158, v154
	s_waitcnt lgkmcnt(1)
	v_lshlrev_b32_e32 v198, 16, v148
	v_and_b32_e32 v199, 0xffff0000, v148
	v_lshlrev_b32_e32 v148, 16, v149
	v_and_b32_e32 v149, 0xffff0000, v149
	v_pk_fma_f32 v[198:199], v[232:233], v[100:101], v[198:199] neg_lo:[1,0,0] neg_hi:[1,0,0]
	v_pk_fma_f32 v[148:149], v[234:235], v[102:103], v[148:149] neg_lo:[1,0,0] neg_hi:[1,0,0]
	s_waitcnt lgkmcnt(0)
	v_pk_mul_f32 v[194:195], v[194:195], v[198:199]
	v_pk_mul_f32 v[148:149], v[196:197], v[148:149]
	v_cvt_pk_bf16_f32 v194, v194, v195
	v_cvt_pk_bf16_f32 v195, v148, v149
	ds_write_b64 v158, v[194:195] offset:4384
	ds_read_b64 v[148:149], v188 offset:53248
	ds_read_b128 v[194:197], v121 offset:128
	s_waitcnt lgkmcnt(1)
	v_lshlrev_b32_e32 v198, 16, v148
	v_and_b32_e32 v199, 0xffff0000, v148
	v_lshlrev_b32_e32 v148, 16, v149
	v_and_b32_e32 v149, 0xffff0000, v149
	v_pk_fma_f32 v[72:73], v[72:73], v[88:89], v[198:199] neg_lo:[1,0,0] neg_hi:[1,0,0]
	v_pk_fma_f32 v[74:75], v[74:75], v[90:91], v[148:149] neg_lo:[1,0,0] neg_hi:[1,0,0]
	s_waitcnt lgkmcnt(0)
	v_pk_mul_f32 v[72:73], v[194:195], v[72:73]
	v_pk_mul_f32 v[74:75], v[196:197], v[74:75]
	v_cvt_pk_bf16_f32 v72, v72, v73
	v_cvt_pk_bf16_f32 v73, v74, v75
	ds_write_b64 v158, v[72:73] offset:4416
	ds_read_b64 v[72:73], v189 offset:53248
	s_waitcnt lgkmcnt(0)
	v_lshlrev_b32_e32 v148, 16, v72
	v_and_b32_e32 v149, 0xffff0000, v72
	v_lshlrev_b32_e32 v194, 16, v73
	v_and_b32_e32 v195, 0xffff0000, v73
	ds_read_b128 v[72:75], v121 offset:192
	v_pk_fma_f32 v[68:69], v[68:69], v[84:85], v[148:149] neg_lo:[1,0,0] neg_hi:[1,0,0]
	v_pk_fma_f32 v[70:71], v[70:71], v[86:87], v[194:195] neg_lo:[1,0,0] neg_hi:[1,0,0]
	v_add_u32_e32 v121, v159, v157
	v_lshl_add_u64 v[148:149], s[20:21], 1, v[116:117]
	s_waitcnt lgkmcnt(0)
	v_pk_mul_f32 v[68:69], v[72:73], v[68:69]
	v_pk_mul_f32 v[70:71], v[74:75], v[70:71]
	v_cvt_pk_bf16_f32 v68, v68, v69
	v_cvt_pk_bf16_f32 v69, v70, v71
	ds_write_b64 v158, v[68:69] offset:4448
	s_waitcnt lgkmcnt(0)
	ds_read_b128 v[68:71], v119 offset:4352
	ds_read_b128 v[72:75], v119 offset:4416
	ds_read_b128 v[194:197], v121
	v_add_u32_e32 v121, v159, v180
	ds_read_b128 v[232:235], v121
	ds_read_b128 v[240:243], v121 offset:2304
	ds_read_b128 v[244:247], v121 offset:2368
	ds_read_b128 v[248:251], v121 offset:4608
	ds_read_b128 v[198:201], v121 offset:4672
	v_add_u32_e32 v121, 0x1000, v158
	s_waitcnt lgkmcnt(5)
	v_mfma_f32_16x16x32_bf16 v[194:197], v[194:197], v[68:71], 0
	s_waitcnt lgkmcnt(4)
	v_mfma_f32_16x16x32_bf16 v[232:235], v[232:235], v[68:71], 0
	s_waitcnt lgkmcnt(3)
	v_mfma_f32_16x16x32_bf16 v[240:243], v[240:243], v[68:71], 0
	s_waitcnt lgkmcnt(2)
	v_mfma_f32_16x16x32_bf16 v[240:243], v[244:247], v[72:75], v[240:243]
	s_waitcnt lgkmcnt(1)
	v_mfma_f32_16x16x32_bf16 v[248:251], v[248:251], v[68:71], 0
	s_waitcnt lgkmcnt(0)
	v_mfma_f32_16x16x32_bf16 v[248:251], v[198:201], v[72:75], v[248:251]
	v_cvt_pk_bf16_f32 v72, v194, v195
	v_cvt_pk_bf16_f32 v73, v196, v197
	v_cvt_pk_bf16_f32 v74, v232, v233
	v_cvt_pk_bf16_f32 v75, v234, v235
	ds_write2_b64 v121, v[72:73], v[74:75] offset0:32 offset1:36
	v_cvt_pk_bf16_f32 v72, v240, v241
	v_cvt_pk_bf16_f32 v73, v242, v243
	s_nop 1
	v_cvt_pk_bf16_f32 v68, v248, v249
	v_cvt_pk_bf16_f32 v69, v250, v251
	ds_write2_b64 v121, v[72:73], v[68:69] offset0:40 offset1:44
	s_waitcnt lgkmcnt(0)
	s_barrier
; #define LAS __attribute__((address_space(3)))
; __device__ __forceinline__ bf16_t f2bf(float f) { return (bf16_t)(pk2(f, f) & 0xFFFFu); }
; #define MFMA16(a, b, c) __builtin_amdgcn_mfma_f32_16x16x32_bf16((a), (b), (c), 0, 0, 0)
; template <int MODE>
; __device__ NOINL void chain_item(const LAS Params* lp, int l, int item, bool ctx_out, LAS unsigned char* lds) {
;     ...
;             Bv[0] = *(const LAS bf16x8*)(RP + fr * 72 + fq * 8); Bv[1] = *(const LAS bf16x8*)(RP + fr * 72 + 32 + fq * 8);
;         } else {
;             Bv[0] = *(const LAS bf16x8*)(VT + (dvrow + fr) * 72 + ((fq ^ vkey) << 3)); Bv[1] = *(const LAS bf16x8*)(VT + (dvrow + fr) * 72 + (((4 + fq) ^ vkey) << 3));
;         }
;         {
;             typedef __attribute__((address_space(1))) bf16_t gbf16;
;             bf16_t* ob; int ldo;
;             if (MODE == 0) { if (dir == 0) { ob = p.hbuf + 256 + h * 128 + 16 * w; ldo = 1024; } else { ob = p.hyproj + h * 128 + 16 * w; ldo = 768; } }
;             else { if (dir == 0) { ob = p.hbuf + 768 + (h + hh) * 64 + 16 * (w & 3); ldo = 1024; } else { ob = p.hyproj + 512 + (h + hh) * 64 + 16 * (w & 3); ldo = 768; } }
; #pragma unroll
;             for (int ct = 0; ct < 4; ++ct) {
;                 f32x4 acc = {0.f, 0.f, 0.f, 0.f};
; #pragma unroll
;                 for (int ks = 0; ks < 2; ++ks) { const bf16x8 A = *(const LAS bf16x8*)(AT + hh * 4608 + (16 * ct + fr) * 72 + ks * 32 + fq * 8); acc = MFMA16(A, Bv[ks], acc); }
;                 gbf16* og = (gbf16*)ob + (size_t)row0 * ldo + fr;
; #pragma unroll
;                 for (int j = 0; j < 4; ++j) { const int c = 16 * ct + 4 * fq + j, tok = dir ? 63 - c : c; og[tok * ldo] = f2bf(eg[ct][j] * qs[ct][j] + acc[j]); }
;             }
;         }
;         {
;             const float gl = MODE == 0 ? gcs[128 + 63] : __expf(64.f * lg);
; #pragma unroll
;             for (int dk = 0; dk < NDK; ++dk) {
;                 Sacc[dk] = Sacc[dk] * gl;
; #pragma unroll
;                 for (int ks = 0; ks < 2; ++ks) { const bf16x8 A = *(const LAS bf16x8*)(KT + (kcol + 16 * dk + fr) * 72 + (((ks * 4 + fq) ^ (((kcol >> 4) + dk) & 7)) << 3)); Sacc[dk] = MFMA16(A, Bv[ks], Sacc[dk]); }
	ds_read_b128 v[72:75], v119 offset:4352
	ds_read_b128 v[68:71], v119 offset:4416
	v_add_u32_e32 v218, v160, v157
	v_add_u32_e32 v219, v160, v180
	v_mov_b32_e32 v119, v1
	v_mov_b32_e32 v121, v1
	ds_read_b128 v[194:197], v218
	ds_read_b128 v[232:235], v219
	ds_read_b128 v[244:247], v219 offset:2304
	ds_read_b128 v[236:239], v219 offset:4608
	ds_read_b128 v[198:201], v218 offset:64
	ds_read_b128 v[240:243], v219 offset:64
	ds_read_b128 v[248:251], v219 offset:2368
	s_waitcnt lgkmcnt(6)
	v_mfma_f32_16x16x32_bf16 v[194:197], v[194:197], v[72:75], 0
	s_waitcnt lgkmcnt(5)
	v_mfma_f32_16x16x32_bf16 v[232:235], v[232:235], v[72:75], 0
	s_waitcnt lgkmcnt(4)
	v_mfma_f32_16x16x32_bf16 v[244:247], v[244:247], v[72:75], 0
	s_waitcnt lgkmcnt(3)
	v_mfma_f32_16x16x32_bf16 v[236:239], v[236:239], v[72:75], 0
	s_waitcnt lgkmcnt(2)
	v_mfma_f32_16x16x32_bf16 v[194:197], v[198:201], v[68:71], v[194:197]
	ds_read_b128 v[198:201], v219 offset:4672
	s_waitcnt lgkmcnt(2)
	v_mfma_f32_16x16x32_bf16 v[232:235], v[240:243], v[68:71], v[232:235]
	s_waitcnt lgkmcnt(1)
	v_mfma_f32_16x16x32_bf16 v[244:247], v[248:251], v[68:71], v[244:247]
	s_waitcnt lgkmcnt(0)
	v_mfma_f32_16x16x32_bf16 v[236:239], v[198:201], v[68:71], v[236:239]
	v_lshl_add_u64 v[240:241], v[148:149], 0, v[0:1]
	v_lshl_add_u64 v[242:243], v[148:149], 0, v[118:119]
	v_lshl_add_u64 v[248:249], v[148:149], 0, v[120:121]
	v_lshl_add_u64 v[250:251], v[148:149], 0, v[122:123]
	s_nop 3
	v_fma_f32 v194, v96, v104, v194
	v_fma_f32 v195, v97, v105, v195
	v_fma_f32 v196, v98, v106, v196
	v_fma_f32 v197, v99, v107, v197
	v_cvt_pk_bf16_f32 v194, v194, v194
	v_cvt_pk_bf16_f32 v195, v195, v195
	v_cvt_pk_bf16_f32 v196, v196, v196
	v_cvt_pk_bf16_f32 v197, v197, v197
	global_store_short v[240:241], v194, off
	global_store_short v[242:243], v195, off
	global_store_short v[248:249], v196, off
	global_store_short v[250:251], v197, off
	v_lshl_add_u64 v[240:241], v[148:149], 0, v[124:125]
	v_lshl_add_u64 v[242:243], v[148:149], 0, v[126:127]
	v_lshl_add_u64 v[248:249], v[148:149], 0, v[128:129]
	v_lshl_add_u64 v[250:251], v[148:149], 0, v[130:131]
	v_fma_f32 v232, v92, v100, v232
	v_fma_f32 v233, v93, v101, v233
	v_fma_f32 v234, v94, v102, v234
	v_fma_f32 v235, v95, v103, v235
	v_cvt_pk_bf16_f32 v232, v232, v232
	v_cvt_pk_bf16_f32 v233, v233, v233
	v_cvt_pk_bf16_f32 v234, v234, v234
	v_cvt_pk_bf16_f32 v235, v235, v235
	global_store_short v[240:241], v232, off
	global_store_short v[242:243], v233, off
	global_store_short v[248:249], v234, off
	global_store_short v[250:251], v235, off
	v_lshl_add_u64 v[240:241], v[148:149], 0, v[132:133]
	v_lshl_add_u64 v[242:243], v[148:149], 0, v[134:135]
	v_lshl_add_u64 v[248:249], v[148:149], 0, v[136:137]
	v_lshl_add_u64 v[250:251], v[148:149], 0, v[138:139]
	v_fma_f32 v244, v80, v88, v244
	v_fma_f32 v245, v81, v89, v245
	v_fma_f32 v246, v82, v90, v246
	v_fma_f32 v247, v83, v91, v247
	v_cvt_pk_bf16_f32 v244, v244, v244
	v_cvt_pk_bf16_f32 v245, v245, v245
	v_cvt_pk_bf16_f32 v246, v246, v246
	v_cvt_pk_bf16_f32 v247, v247, v247
	global_store_short v[240:241], v244, off
	global_store_short v[242:243], v245, off
	global_store_short v[248:249], v246, off
	global_store_short v[250:251], v247, off
	v_lshl_add_u64 v[240:241], v[148:149], 0, v[140:141]
	v_lshl_add_u64 v[242:243], v[148:149], 0, v[142:143]
	v_lshl_add_u64 v[248:249], v[148:149], 0, v[144:145]
	v_lshl_add_u64 v[250:251], v[148:149], 0, v[146:147]
	v_fma_f32 v236, v76, v84, v236
	v_fma_f32 v237, v77, v85, v237
	v_fma_f32 v238, v78, v86, v238
	v_fma_f32 v239, v79, v87, v239
	v_cvt_pk_bf16_f32 v236, v236, v236
	v_cvt_pk_bf16_f32 v237, v237, v237
	v_cvt_pk_bf16_f32 v238, v238, v238
	v_cvt_pk_bf16_f32 v239, v239, v239
	global_store_short v[240:241], v236, off
	global_store_short v[242:243], v237, off
	global_store_short v[248:249], v238, off
	global_store_short v[250:251], v239, off
	v_mov_b32_e32 v76, s17
	ds_read_b32 v76, v76
	v_add_u32_e32 v83, v161, v155
	v_add_u32_e32 v82, v181, v182
	v_add_u32_e32 v84, v161, v182
	v_add_u32_e32 v85, v161, v183
	v_add_u32_e32 v86, v161, v162
	ds_read_b128 v[88:91], v83 offset:34816
	ds_read_b128 v[92:95], v82 offset:34816
	ds_read_b128 v[96:99], v190 offset:34816
	ds_read_b128 v[100:103], v191 offset:34816
	ds_read_b128 v[104:107], v83 offset:44096
	ds_read_b128 v[194:197], v84 offset:46400
	ds_read_b128 v[198:201], v85 offset:48704
	ds_read_b128 v[232:235], v86 offset:51008
	s_waitcnt lgkmcnt(8)
; #define LAS __attribute__((address_space(3)))
; #define MFMA16(a, b, c) __builtin_amdgcn_mfma_f32_16x16x32_bf16((a), (b), (c), 0, 0, 0)
; template <int MODE>
; __device__ NOINL void chain_item(const LAS Params* lp, int l, int item, bool ctx_out, LAS unsigned char* lds) {
;     ...
;         {
;             const float gl = MODE == 0 ? gcs[128 + 63] : __expf(64.f * lg);
; #pragma unroll
;             for (int dk = 0; dk < NDK; ++dk) {
;                 Sacc[dk] = Sacc[dk] * gl;
; #pragma unroll
;                 for (int ks = 0; ks < 2; ++ks) { const bf16x8 A = *(const LAS bf16x8*)(KT + (kcol + 16 * dk + fr) * 72 + (((ks * 4 + fq) ^ (((kcol >> 4) + dk) & 7)) << 3)); Sacc[dk] = MFMA16(A, Bv[ks], Sacc[dk]); }
;             }
;         }
;     }
	v_pk_mul_f32 v[30:31], v[30:31], v[76:77] op_sel_hi:[1,0]
	v_pk_mul_f32 v[28:29], v[28:29], v[76:77] op_sel_hi:[1,0]
	v_pk_mul_f32 v[42:43], v[42:43], v[76:77] op_sel_hi:[1,0]
	v_pk_mul_f32 v[40:41], v[40:41], v[76:77] op_sel_hi:[1,0]
	v_pk_mul_f32 v[34:35], v[34:35], v[76:77] op_sel_hi:[1,0]
	v_pk_mul_f32 v[32:33], v[32:33], v[76:77] op_sel_hi:[1,0]
	v_pk_mul_f32 v[38:39], v[38:39], v[76:77] op_sel_hi:[1,0]
	v_pk_mul_f32 v[36:37], v[36:37], v[76:77] op_sel_hi:[1,0]
	v_pk_mul_f32 v[58:59], v[58:59], v[76:77] op_sel_hi:[1,0]
	v_pk_mul_f32 v[56:57], v[56:57], v[76:77] op_sel_hi:[1,0]
	v_pk_mul_f32 v[54:55], v[54:55], v[76:77] op_sel_hi:[1,0]
	v_pk_mul_f32 v[52:53], v[52:53], v[76:77] op_sel_hi:[1,0]
	v_pk_mul_f32 v[46:47], v[46:47], v[76:77] op_sel_hi:[1,0]
	v_pk_mul_f32 v[44:45], v[44:45], v[76:77] op_sel_hi:[1,0]
	v_pk_mul_f32 v[50:51], v[50:51], v[76:77] op_sel_hi:[1,0]
	v_pk_mul_f32 v[48:49], v[48:49], v[76:77] op_sel_hi:[1,0]
	s_waitcnt lgkmcnt(7)
	v_mfma_f32_16x16x32_bf16 v[28:31], v[88:91], v[72:75], v[28:31]
	ds_read_b128 v[88:91], v83 offset:34880
	s_waitcnt lgkmcnt(7)
	v_mfma_f32_16x16x32_bf16 v[40:43], v[92:95], v[72:75], v[40:43]
	ds_read_b128 v[92:95], v82 offset:34880
	s_waitcnt lgkmcnt(7)
	v_mfma_f32_16x16x32_bf16 v[32:35], v[96:99], v[72:75], v[32:35]
	ds_read_b128 v[96:99], v190 offset:34880
	s_waitcnt lgkmcnt(7)
	v_mfma_f32_16x16x32_bf16 v[36:39], v[100:103], v[72:75], v[36:39]
	ds_read_b128 v[100:103], v191 offset:34880
	s_waitcnt lgkmcnt(7)
	v_mfma_f32_16x16x32_bf16 v[56:59], v[104:107], v[72:75], v[56:59]
	ds_read_b128 v[104:107], v83 offset:44032
	s_waitcnt lgkmcnt(7)
	v_mfma_f32_16x16x32_bf16 v[52:55], v[194:197], v[72:75], v[52:55]
	ds_read_b128 v[194:197], v84 offset:46336
	s_waitcnt lgkmcnt(7)
	v_mfma_f32_16x16x32_bf16 v[44:47], v[198:201], v[72:75], v[44:47]
	ds_read_b128 v[198:201], v85 offset:48640
	s_waitcnt lgkmcnt(7)
	v_mfma_f32_16x16x32_bf16 v[48:51], v[232:235], v[72:75], v[48:51]
	ds_read_b128 v[232:235], v86 offset:50944
	s_waitcnt lgkmcnt(7)
	v_mfma_f32_16x16x32_bf16 v[28:31], v[88:91], v[68:71], v[28:31]
	s_waitcnt lgkmcnt(6)
	v_mfma_f32_16x16x32_bf16 v[40:43], v[92:95], v[68:71], v[40:43]
	s_waitcnt lgkmcnt(5)
	v_mfma_f32_16x16x32_bf16 v[32:35], v[96:99], v[68:71], v[32:35]
	s_waitcnt lgkmcnt(4)
	v_mfma_f32_16x16x32_bf16 v[36:39], v[100:103], v[68:71], v[36:39]
	s_waitcnt lgkmcnt(3)
	v_mfma_f32_16x16x32_bf16 v[56:59], v[104:107], v[68:71], v[56:59]
	s_waitcnt lgkmcnt(2)
	v_mfma_f32_16x16x32_bf16 v[52:55], v[194:197], v[68:71], v[52:55]
	s_waitcnt lgkmcnt(1)
	v_mfma_f32_16x16x32_bf16 v[44:47], v[198:201], v[68:71], v[44:47]
	s_waitcnt lgkmcnt(0)
	v_mfma_f32_16x16x32_bf16 v[48:51], v[232:235], v[68:71], v[48:51]
	s_waitcnt vmcnt(19)
	v_mov_b64_e32 v[74:75], v[66:67]
	v_mov_b64_e32 v[70:71], v[62:63]
	v_mov_b64_e32 v[72:73], v[64:65]
	v_mov_b64_e32 v[68:69], v[60:61]
	s_cbranch_scc0 .LBB0_1135
